# FFN-down / out-projection k-loops unrolled by two: LDS stage offsets as instruction immediates, per-tile address registers, no per-k-tile LDS address arithmetic
# speedup vs baseline: 1.0008x; 1.0008x over previous
.LBB0_759:
	s_lshr_b32 s6, s28, 3
	s_and_b32 s29, s6, 24
	s_lshl_b32 s6, s29, 3
	s_sub_i32 s6, s28, s6
	s_ashr_i32 s17, s6, 3
	s_and_b32 s6, s28, 7
	s_or_b32 s6, s6, s3
	s_or_b32 s16, s6, s29
	v_mad_i64_i32 v[34:35], s[6:7], s17, v171, v[116:117]
	s_mul_i32 s10, s16, 0xb0000
	v_lshl_add_u64 v[36:37], v[118:119], 0, s[10:11]
	v_add_co_u32_e32 v22, vcc, s21, v34
	v_lshl_add_u64 v[2:3], v[36:37], 0, v[130:131]
	v_lshl_add_u64 v[10:11], v[36:37], 0, v[132:133]
	v_addc_co_u32_e32 v23, vcc, 0, v35, vcc
	v_lshl_add_u64 v[14:15], v[36:37], 0, v[134:135]
	s_barrier
	global_load_dwordx4 v[2:5], v[2:3], off
	s_waitcnt lgkmcnt(0)
	global_load_dwordx4 v[6:9], v[34:35], off
	s_nop 0
	global_load_dwordx4 v[10:13], v[10:11], off
	s_nop 0
	global_load_dwordx4 v[14:17], v[14:15], off
	s_nop 0
	global_load_dwordx4 v[18:21], v[22:23], off offset:-4096
	s_nop 0
	global_load_dwordx4 v[22:25], v[22:23], off
	v_add_co_u32_e32 v38, vcc, s22, v34
	v_lshl_add_u64 v[26:27], v[36:37], 0, v[136:137]
	s_nop 0
	v_addc_co_u32_e32 v39, vcc, 0, v35, vcc
	v_add_co_u32_e32 v44, vcc, s23, v34
	v_lshl_add_u64 v[36:37], v[36:37], 0, s[12:13]
	s_nop 0
	v_addc_co_u32_e32 v45, vcc, 0, v35, vcc
	global_load_dwordx4 v[26:29], v[26:27], off
	v_lshl_add_u64 v[40:41], v[36:37], 0, v[130:131]
	v_lshl_add_u64 v[42:43], v[36:37], 0, v[132:133]
	v_lshl_add_u64 v[46:47], v[36:37], 0, v[134:135]
	v_lshl_add_u64 v[36:37], v[36:37], 0, v[136:137]
	v_add_co_u32_e32 v34, vcc, 0x7000, v34
	global_load_dwordx4 v[30:33], v[38:39], off offset:-4096
	global_load_dwordx4 v[90:93], v[40:41], off
	global_load_dwordx4 v[94:97], v[38:39], off
	global_load_dwordx4 v[82:85], v[42:43], off
	global_load_dwordx4 v[70:73], v[46:47], off
	global_load_dwordx4 v[86:89], v[44:45], off offset:-4096
	global_load_dwordx4 v[74:77], v[44:45], off
	v_addc_co_u32_e32 v35, vcc, 0, v35, vcc
	global_load_dwordx4 v[66:69], v[36:37], off
	global_load_dwordx4 v[78:81], v[34:35], off
	s_and_b32 s6, s2, 7
	s_add_i32 s7, s3, s29
	s_add_i32 s29, s7, s6
	s_mov_b64 s[14:15], 0
	s_mov_b32 s10, 0
	v_mad_u64_u32 v[138:139], s[6:7], s29, v171, v[122:123]
	v_mad_u64_u32 v[140:141], s[6:7], s29, v171, v[124:125]
	v_mad_u64_u32 v[142:143], s[6:7], s29, v171, v[126:127]
	v_mad_u64_u32 v[144:145], s[6:7], s29, v171, v[128:129]
	v_mad_i64_i32 v[146:147], s[6:7], s17, v171, v[120:121]
	v_mov_b32_e32 v34, v115
	v_mov_b32_e32 v35, v115
	v_mov_b32_e32 v36, v115
	v_mov_b32_e32 v37, v115
	v_mov_b32_e32 v38, v115
	v_mov_b32_e32 v39, v115
	v_mov_b32_e32 v40, v115
	v_mov_b32_e32 v41, v115
	v_mov_b32_e32 v42, v115
	v_mov_b32_e32 v43, v115
	v_mov_b32_e32 v44, v115
	v_mov_b32_e32 v45, v115
	v_mov_b32_e32 v46, v115
	v_mov_b32_e32 v47, v115
	v_mov_b32_e32 v48, v115
	v_mov_b32_e32 v49, v115
	v_mov_b32_e32 v50, v115
	v_mov_b32_e32 v51, v115
	v_mov_b32_e32 v52, v115
	v_mov_b32_e32 v53, v115
	v_mov_b32_e32 v54, v115
	v_mov_b32_e32 v55, v115
	v_mov_b32_e32 v56, v115
	v_mov_b32_e32 v57, v115
	v_mov_b32_e32 v58, v115
	v_mov_b32_e32 v59, v115
	v_mov_b32_e32 v60, v115
	s_waitcnt vmcnt(15)
	ds_write_b128 v150, v[2:5]
	s_waitcnt vmcnt(14)
	ds_write_b128 v150, v[6:9] offset:18432
	s_waitcnt vmcnt(13)
	ds_write_b128 v152, v[10:13]
	s_waitcnt vmcnt(11)
	ds_write_b128 v152, v[18:21] offset:18432
	ds_write_b128 v154, v[14:17]
	s_waitcnt vmcnt(10)
	ds_write_b128 v154, v[22:25] offset:18432
	s_waitcnt vmcnt(9)
	ds_write_b128 v156, v[26:29]
	s_waitcnt vmcnt(8)
	ds_write_b128 v156, v[30:33] offset:18432
	s_waitcnt lgkmcnt(0)
	s_barrier
	ds_read_b128 v[98:101], v172 offset:4608
	ds_read_b128 v[110:113], v172
	ds_read_b128 v[102:105], v173 offset:23040
	ds_read_b128 v[106:109], v173 offset:18432
	v_mov_b32_e32 v2, v115
	v_mov_b32_e32 v3, v115
	v_mov_b32_e32 v4, v115
	v_mov_b32_e32 v5, v115
	v_mov_b32_e32 v6, v115
	v_mov_b32_e32 v7, v115
	v_mov_b32_e32 v8, v115
	v_mov_b32_e32 v9, v115
	v_mov_b32_e32 v10, v115
	v_mov_b32_e32 v11, v115
	v_mov_b32_e32 v12, v115
	v_mov_b32_e32 v13, v115
	v_mov_b32_e32 v14, v115
	v_mov_b32_e32 v15, v115
	v_mov_b32_e32 v16, v115
	v_mov_b32_e32 v17, v115
	v_mov_b32_e32 v18, v115
	v_mov_b32_e32 v19, v115
	v_mov_b32_e32 v20, v115
	v_mov_b32_e32 v21, v115
	v_mov_b32_e32 v22, v115
	v_mov_b32_e32 v23, v115
	v_mov_b32_e32 v24, v115
	v_mov_b32_e32 v25, v115
	v_mov_b32_e32 v26, v115
	v_mov_b32_e32 v27, v115
	v_mov_b32_e32 v28, v115
	v_mov_b32_e32 v29, v115
	v_mov_b32_e32 v30, v115
	v_mov_b32_e32 v31, v115
	v_mov_b32_e32 v32, v115
	v_mov_b32_e32 v33, v115
	v_mov_b32_e32 v61, v115
	v_mov_b32_e32 v62, v115
	v_mov_b32_e32 v63, v115
	v_mov_b32_e32 v64, v115
	v_mov_b32_e32 v65, v115
	v_subrev_u32_e32 v240, s34, v138
	v_subrev_u32_e32 v241, s34, v140
	v_subrev_u32_e32 v242, s34, v142
	v_subrev_u32_e32 v243, s34, v144
	v_subrev_u32_e32 v244, s34, v146
	v_lshlrev_b32_e32 v251, 1, v148
	v_lshl_add_u32 v245, v149, 1, v251
	v_lshl_add_u32 v246, v151, 1, v251
	v_lshl_add_u32 v247, v153, 1, v251
	v_lshl_add_u32 v248, v155, 1, v251
	v_add_u32_e32 v249, v157, v159
	v_add_u32_e32 v250, v158, v159
.LBB0_760:
	s_add_u32 s62, s34, s14
	s_addc_u32 s63, s35, s15
	s_add_u32 s64, s62, s24
	s_addc_u32 s65, s63, 0
	s_add_u32 s76, s62, s25
	s_addc_u32 s77, s63, 0
	s_waitcnt lgkmcnt(0)
	v_mfma_f32_32x32x16_bf16 v[50:65], v[106:109], v[110:113], v[50:65]
	s_waitcnt vmcnt(7)
	ds_write_b128 v245, v[90:93] offset:36864
	s_waitcnt vmcnt(6)
	ds_write_b128 v245, v[94:97] offset:55296
	v_mfma_f32_32x32x16_bf16 v[34:49], v[102:105], v[110:113], v[34:49]
	s_waitcnt vmcnt(5)
	ds_write_b128 v246, v[82:85] offset:36864
	s_waitcnt vmcnt(3)
	ds_write_b128 v246, v[86:89] offset:55296
	v_mfma_f32_32x32x16_bf16 v[18:33], v[106:109], v[98:101], v[18:33]
	s_waitcnt vmcnt(1)
	ds_write_b128 v247, v[70:73] offset:36864
	s_waitcnt vmcnt(2)
	ds_write_b128 v247, v[74:77] offset:55296
	v_mfma_f32_32x32x16_bf16 v[2:17], v[102:105], v[98:101], v[2:17]
	s_waitcnt vmcnt(0)
	ds_write_b128 v248, v[66:69] offset:36864
	s_waitcnt vmcnt(0)
	ds_write_b128 v248, v[78:81] offset:55296
	ds_read_b128 v[66:69], v249 offset:23072
	ds_read_b128 v[70:73], v250 offset:4640
	global_load_dwordx4 v[90:93], v240, s[62:63]
	s_waitcnt lgkmcnt(0)
	v_mfma_f32_32x32x16_bf16 v[2:17], v[66:69], v[70:73], v[2:17]
	ds_read_b128 v[74:77], v249 offset:18464
	ds_read_b128 v[98:101], v249 offset:18496
	global_load_dwordx4 v[94:97], v244, s[64:65] offset:-4096
	global_load_dwordx4 v[82:85], v241, s[62:63]
	global_load_dwordx4 v[86:89], v244, s[64:65]
	s_waitcnt lgkmcnt(1)
	v_mfma_f32_32x32x16_bf16 v[18:33], v[74:77], v[70:73], v[18:33]
	ds_read_b128 v[70:73], v250 offset:32
	ds_read_b128 v[102:105], v250 offset:64
	s_add_i32 s10, s10, 1
	s_add_u32 s14, s14, 0x4000
	s_addc_u32 s15, s15, 0
	s_waitcnt lgkmcnt(1)
	v_mfma_f32_32x32x16_bf16 v[50:65], v[74:77], v[70:73], v[50:65]
	ds_read_b128 v[174:177], v249 offset:23104
	ds_read_b128 v[178:181], v250 offset:4672
	global_load_dwordx4 v[74:77], v244, s[76:77] offset:-4096
	s_cmp_eq_u32 s14, 0xa8000
	global_load_dwordx4 v[78:81], v244, s[76:77]
	v_mfma_f32_32x32x16_bf16 v[34:49], v[66:69], v[70:73], v[34:49]
	global_load_dwordx4 v[70:73], v242, s[62:63]
	global_load_dwordx4 v[66:69], v243, s[62:63]
	ds_read_b128 v[182:185], v249 offset:18528
	ds_read_b128 v[186:189], v250 offset:96
	s_waitcnt lgkmcnt(4)
	v_mfma_f32_32x32x16_bf16 v[50:65], v[98:101], v[102:105], v[50:65]
	ds_read_b128 v[190:193], v249 offset:23136
	ds_read_b128 v[194:197], v250 offset:4704
	s_waitcnt lgkmcnt(0)
	s_barrier
	v_mfma_f32_32x32x16_bf16 v[34:49], v[174:177], v[102:105], v[34:49]
	ds_read_b128 v[106:109], v249 offset:55296
	ds_read_b128 v[110:113], v250 offset:36864
	v_mfma_f32_32x32x16_bf16 v[18:33], v[98:101], v[178:181], v[18:33]
	ds_read_b128 v[102:105], v249 offset:59904
	ds_read_b128 v[98:101], v250 offset:41472
	v_mfma_f32_32x32x16_bf16 v[2:17], v[174:177], v[178:181], v[2:17]
	v_mfma_f32_32x32x16_bf16 v[50:65], v[182:185], v[186:189], v[50:65]
	v_mfma_f32_32x32x16_bf16 v[34:49], v[190:193], v[186:189], v[34:49]
	v_mfma_f32_32x32x16_bf16 v[18:33], v[182:185], v[194:197], v[18:33]
	v_mfma_f32_32x32x16_bf16 v[2:17], v[190:193], v[194:197], v[2:17]
	s_cbranch_scc1 .Ldnu_exit_0
	s_add_u32 s62, s34, s14
	s_addc_u32 s63, s35, s15
	s_add_u32 s64, s62, s24
	s_addc_u32 s65, s63, 0
	s_add_u32 s76, s62, s25
	s_addc_u32 s77, s63, 0
	s_waitcnt lgkmcnt(0)
	v_mfma_f32_32x32x16_bf16 v[50:65], v[106:109], v[110:113], v[50:65]
	s_waitcnt vmcnt(7)
	ds_write_b128 v245, v[90:93]
	s_waitcnt vmcnt(6)
	ds_write_b128 v245, v[94:97] offset:18432
	v_mfma_f32_32x32x16_bf16 v[34:49], v[102:105], v[110:113], v[34:49]
	s_waitcnt vmcnt(5)
	ds_write_b128 v246, v[82:85]
	s_waitcnt vmcnt(3)
	ds_write_b128 v246, v[86:89] offset:18432
	v_mfma_f32_32x32x16_bf16 v[18:33], v[106:109], v[98:101], v[18:33]
	s_waitcnt vmcnt(1)
	ds_write_b128 v247, v[70:73]
	s_waitcnt vmcnt(2)
	ds_write_b128 v247, v[74:77] offset:18432
	v_mfma_f32_32x32x16_bf16 v[2:17], v[102:105], v[98:101], v[2:17]
	s_waitcnt vmcnt(0)
	ds_write_b128 v248, v[66:69]
	s_waitcnt vmcnt(0)
	ds_write_b128 v248, v[78:81] offset:18432
	ds_read_b128 v[66:69], v249 offset:59936
	ds_read_b128 v[70:73], v250 offset:41504
	global_load_dwordx4 v[90:93], v240, s[62:63]
	s_waitcnt lgkmcnt(0)
	v_mfma_f32_32x32x16_bf16 v[2:17], v[66:69], v[70:73], v[2:17]
	ds_read_b128 v[74:77], v249 offset:55328
	ds_read_b128 v[98:101], v249 offset:55360
	global_load_dwordx4 v[94:97], v244, s[64:65] offset:-4096
	global_load_dwordx4 v[82:85], v241, s[62:63]
	global_load_dwordx4 v[86:89], v244, s[64:65]
	s_waitcnt lgkmcnt(1)
	v_mfma_f32_32x32x16_bf16 v[18:33], v[74:77], v[70:73], v[18:33]
	ds_read_b128 v[70:73], v250 offset:36896
	ds_read_b128 v[102:105], v250 offset:36928
	s_add_i32 s10, s10, 1
	s_add_u32 s14, s14, 0x4000
	s_addc_u32 s15, s15, 0
	s_waitcnt lgkmcnt(1)
	v_mfma_f32_32x32x16_bf16 v[50:65], v[74:77], v[70:73], v[50:65]
	ds_read_b128 v[174:177], v249 offset:59968
	ds_read_b128 v[178:181], v250 offset:41536
	global_load_dwordx4 v[74:77], v244, s[76:77] offset:-4096
	s_cmp_eq_u32 s14, 0xa8000
	global_load_dwordx4 v[78:81], v244, s[76:77]
	v_mfma_f32_32x32x16_bf16 v[34:49], v[66:69], v[70:73], v[34:49]
	global_load_dwordx4 v[70:73], v242, s[62:63]
	global_load_dwordx4 v[66:69], v243, s[62:63]
	ds_read_b128 v[182:185], v249 offset:55392
	ds_read_b128 v[186:189], v250 offset:36960
	s_waitcnt lgkmcnt(4)
	v_mfma_f32_32x32x16_bf16 v[50:65], v[98:101], v[102:105], v[50:65]
	ds_read_b128 v[190:193], v249 offset:60000
	ds_read_b128 v[194:197], v250 offset:41568
	s_waitcnt lgkmcnt(0)
	s_barrier
	v_mfma_f32_32x32x16_bf16 v[34:49], v[174:177], v[102:105], v[34:49]
	ds_read_b128 v[106:109], v249 offset:18432
	ds_read_b128 v[110:113], v250
	v_mfma_f32_32x32x16_bf16 v[18:33], v[98:101], v[178:181], v[18:33]
	ds_read_b128 v[102:105], v249 offset:23040
	ds_read_b128 v[98:101], v250 offset:4608
	v_mfma_f32_32x32x16_bf16 v[2:17], v[174:177], v[178:181], v[2:17]
	v_mfma_f32_32x32x16_bf16 v[50:65], v[182:185], v[186:189], v[50:65]
	v_mfma_f32_32x32x16_bf16 v[34:49], v[190:193], v[186:189], v[34:49]
	v_mfma_f32_32x32x16_bf16 v[18:33], v[182:185], v[194:197], v[18:33]
	v_mfma_f32_32x32x16_bf16 v[2:17], v[190:193], v[194:197], v[2:17]
	s_cbranch_scc0 .LBB0_760
.Ldnu_exit_0:
	s_waitcnt lgkmcnt(2)
	v_mfma_f32_32x32x16_bf16 v[50:65], v[106:109], v[110:113], v[50:65]
	s_waitcnt vmcnt(7)
	ds_write_b128 v150, v[90:93] offset:36864
	s_waitcnt vmcnt(6)
	ds_write_b128 v150, v[94:97] offset:55296
	s_lshl_b32 s6, s17, 1
	s_ashr_i32 s7, s6, 31
	s_lshl_b32 s10, s16, 7
	s_lshl_b64 s[6:7], s[6:7], 2
	s_add_u32 s6, s44, s6
	s_waitcnt lgkmcnt(3)
	v_mfma_f32_32x32x16_bf16 v[34:49], v[102:105], v[110:113], v[34:49]
	s_waitcnt vmcnt(5)
	ds_write_b128 v152, v[82:85] offset:36864
	s_waitcnt vmcnt(4)
	ds_write_b128 v152, v[86:89] offset:55296
	s_addc_u32 s7, s45, s7
	s_mov_b64 s[14:15], -1
	s_waitcnt lgkmcnt(4)
	v_mfma_f32_32x32x16_bf16 v[18:33], v[106:109], v[98:101], v[18:33]
	s_waitcnt vmcnt(1)
	ds_write_b128 v154, v[70:73] offset:36864
	ds_write_b128 v154, v[74:77] offset:55296
	v_mfma_f32_32x32x16_bf16 v[2:17], v[102:105], v[98:101], v[2:17]
	s_waitcnt vmcnt(0)
	ds_write_b128 v156, v[66:69] offset:36864
	ds_write_b128 v156, v[78:81] offset:55296
	ds_read_b128 v[66:69], v169 offset:23072
	ds_read_b128 v[70:73], v170 offset:4640
	s_waitcnt lgkmcnt(0)
	v_mfma_f32_32x32x16_bf16 v[2:17], v[66:69], v[70:73], v[2:17]
	ds_read_b128 v[74:77], v169 offset:18464
	ds_read_b128 v[78:81], v169 offset:18496
	s_waitcnt lgkmcnt(1)
	v_mfma_f32_32x32x16_bf16 v[18:33], v[74:77], v[70:73], v[18:33]
	ds_read_b128 v[70:73], v170 offset:32
	ds_read_b128 v[82:85], v170 offset:64
	s_waitcnt lgkmcnt(1)
	v_mfma_f32_32x32x16_bf16 v[50:65], v[74:77], v[70:73], v[50:65]
	ds_read_b128 v[74:77], v169 offset:23104
	ds_read_b128 v[86:89], v170 offset:4672
	v_mfma_f32_32x32x16_bf16 v[34:49], v[66:69], v[70:73], v[34:49]
	ds_read_b128 v[66:69], v169 offset:18528
	ds_read_b128 v[70:73], v170 offset:96
	s_waitcnt lgkmcnt(4)
	v_mfma_f32_32x32x16_bf16 v[50:65], v[78:81], v[82:85], v[50:65]
	ds_read_b128 v[90:93], v169 offset:23136
	ds_read_b128 v[94:97], v170 offset:4704
	s_waitcnt lgkmcnt(0)
	s_barrier
	v_mfma_f32_32x32x16_bf16 v[34:49], v[74:77], v[82:85], v[34:49]
	ds_read_b128 v[82:85], v173 offset:55296
	ds_read_b128 v[98:101], v172 offset:36864
	v_mfma_f32_32x32x16_bf16 v[18:33], v[78:81], v[86:89], v[18:33]
	ds_read_b128 v[78:81], v173 offset:59904
	ds_read_b128 v[102:105], v172 offset:41472
	v_mfma_f32_32x32x16_bf16 v[2:17], v[74:77], v[86:89], v[2:17]
	ds_read_b128 v[74:77], v169 offset:59936
	ds_read_b128 v[86:89], v170 offset:41504
	v_mfma_f32_32x32x16_bf16 v[50:65], v[66:69], v[70:73], v[50:65]
	ds_read_b128 v[106:109], v169 offset:55328
	ds_read_b128 v[110:113], v169 offset:55360
	v_mfma_f32_32x32x16_bf16 v[34:49], v[90:93], v[70:73], v[34:49]
	ds_read_b128 v[70:73], v170 offset:36896
	ds_read_b128 v[138:141], v170 offset:36928
	v_mfma_f32_32x32x16_bf16 v[18:33], v[66:69], v[94:97], v[18:33]
	ds_read_b128 v[66:69], v169 offset:59968
	ds_read_b128 v[142:145], v170 offset:41536
	v_mfma_f32_32x32x16_bf16 v[2:17], v[90:93], v[94:97], v[2:17]
	ds_read_b128 v[90:93], v169 offset:55392
	ds_read_b128 v[94:97], v170 offset:36960
	s_waitcnt lgkmcnt(12)
	v_mfma_f32_32x32x16_bf16 v[50:65], v[82:85], v[98:101], v[50:65]
	ds_read_b128 v[174:177], v169 offset:60000
	ds_read_b128 v[178:181], v170 offset:41568
	s_waitcnt lgkmcnt(0)
	s_barrier
	s_barrier
	v_mfma_f32_32x32x16_bf16 v[34:49], v[78:81], v[98:101], v[34:49]
	v_mfma_f32_32x32x16_bf16 v[18:33], v[82:85], v[102:105], v[18:33]
	v_mfma_f32_32x32x16_bf16 v[2:17], v[78:81], v[102:105], v[2:17]
	v_mfma_f32_32x32x16_bf16 v[50:65], v[106:109], v[70:73], v[50:65]
	v_mfma_f32_32x32x16_bf16 v[34:49], v[74:77], v[70:73], v[34:49]
	v_mfma_f32_32x32x16_bf16 v[18:33], v[106:109], v[86:89], v[18:33]
	v_mfma_f32_32x32x16_bf16 v[2:17], v[74:77], v[86:89], v[2:17]
	v_mfma_f32_32x32x16_bf16 v[50:65], v[110:113], v[138:141], v[50:65]
	v_mfma_f32_32x32x16_bf16 v[34:49], v[66:69], v[138:141], v[34:49]
	v_mfma_f32_32x32x16_bf16 v[18:33], v[110:113], v[142:145], v[18:33]
	v_mfma_f32_32x32x16_bf16 v[2:17], v[66:69], v[142:145], v[2:17]
	v_mfma_f32_32x32x16_bf16 v[50:65], v[90:93], v[94:97], v[50:65]
	s_nop 11
	ds_write_b128 v160, v[50:53]
	ds_write_b128 v160, v[54:57] offset:32
	v_mfma_f32_32x32x16_bf16 v[34:49], v[174:177], v[94:97], v[34:49]
	ds_write_b128 v160, v[58:61] offset:64
	ds_write_b128 v160, v[62:65] offset:96
	v_mfma_f32_32x32x16_bf16 v[18:33], v[90:93], v[178:181], v[18:33]
	s_nop 8
	ds_write_b128 v160, v[34:37] offset:128
	ds_write_b128 v160, v[38:41] offset:160
	v_mfma_f32_32x32x16_bf16 v[2:17], v[174:177], v[178:181], v[2:17]
	ds_write_b128 v160, v[42:45] offset:192
	ds_write_b128 v160, v[46:49] offset:224
	ds_write_b128 v160, v[18:21] offset:16896
	ds_write_b128 v160, v[22:25] offset:16928
	ds_write_b128 v160, v[26:29] offset:16960
	ds_write_b128 v160, v[30:33] offset:16992
	v_or_b32_e32 v20, s10, v1
	s_nop 4
	ds_write_b128 v160, v[2:5] offset:17024
	v_lshl_or_b32 v2, s17, 7, v161
	v_ashrrev_i32_e32 v21, 6, v2
	v_lshl_add_u32 v2, s16, 4, v21
	v_ashrrev_i32_e32 v3, 31, v2
	v_lshlrev_b64 v[2:3], 14, v[2:3]
	v_lshl_add_u64 v[2:3], s[92:93], 0, v[2:3]
	v_lshl_add_u64 v[4:5], v[2:3], 0, v[114:115]
	s_mov_b32 s16, 0
	ds_write_b128 v160, v[6:9] offset:17056
	ds_write_b128 v160, v[10:13] offset:17088
	ds_write_b128 v160, v[14:17] offset:17120
	s_waitcnt lgkmcnt(0)
	s_barrier
	s_branch .LBB0_763

.LBB0_2271:
	s_lshr_b32 s6, s26, 3
	s_and_b32 s6, s6, 24
	s_add_i32 s7, s3, s6
	s_and_b32 s10, s2, 7
	s_add_i32 s7, s7, s10
	s_lshl_b32 s10, s7, 18
	s_lshl_b32 s7, s6, 3
	s_sub_i32 s7, s26, s7
	s_ashr_i32 s14, s7, 3
	s_and_b32 s7, s26, 7
	s_or_b32 s7, s7, s3
	s_or_b32 s27, s7, s6
	v_lshl_add_u64 v[138:139], v[122:123], 0, s[10:11]
	v_lshl_add_u64 v[140:141], v[124:125], 0, s[10:11]
	v_lshl_add_u64 v[142:143], v[126:127], 0, s[10:11]
	v_lshl_add_u64 v[144:145], v[128:129], 0, s[10:11]
	s_ashr_i32 s15, s14, 31
	s_lshl_b32 s10, s27, 18
	s_lshl_b64 s[6:7], s[14:15], 18
	v_lshl_add_u64 v[6:7], v[118:119], 0, s[10:11]
	v_lshl_add_u64 v[4:5], v[116:117], 0, s[6:7]
	v_lshl_add_u64 v[2:3], v[6:7], 0, v[130:131]
	s_waitcnt vmcnt(63) expcnt(7) lgkmcnt(15)
	s_barrier
	s_waitcnt lgkmcnt(0)
	global_load_dwordx4 v[8:11], v[2:3], off
	global_load_dwordx4 v[12:15], v[4:5], off
	v_lshl_add_u64 v[2:3], v[6:7], 0, v[132:133]
	v_add_co_u32_e32 v32, vcc, s21, v4
	v_lshl_add_u64 v[34:35], v[6:7], 0, v[134:135]
	s_nop 0
	v_addc_co_u32_e32 v33, vcc, 0, v5, vcc
	global_load_dwordx4 v[16:19], v[2:3], off
	global_load_dwordx4 v[20:23], v[34:35], off
	global_load_dwordx4 v[24:27], v[32:33], off offset:-4096
	global_load_dwordx4 v[28:31], v[32:33], off
	v_add_co_u32_e32 v40, vcc, s22, v4
	v_lshl_add_u64 v[2:3], v[6:7], 0, v[136:137]
	s_nop 0
	v_addc_co_u32_e32 v41, vcc, 0, v5, vcc
	v_add_co_u32_e32 v46, vcc, s23, v4
	v_lshl_add_u64 v[6:7], v[6:7], 0, s[12:13]
	s_nop 0
	v_addc_co_u32_e32 v47, vcc, 0, v5, vcc
	global_load_dwordx4 v[32:35], v[2:3], off
	v_lshl_add_u64 v[42:43], v[6:7], 0, v[130:131]
	v_lshl_add_u64 v[44:45], v[6:7], 0, v[132:133]
	v_lshl_add_u64 v[48:49], v[6:7], 0, v[134:135]
	v_lshl_add_u64 v[6:7], v[6:7], 0, v[136:137]
	v_add_co_u32_e32 v4, vcc, 0x7000, v4
	global_load_dwordx4 v[36:39], v[40:41], off offset:-4096
	global_load_dwordx4 v[90:93], v[42:43], off
	global_load_dwordx4 v[94:97], v[40:41], off
	global_load_dwordx4 v[82:85], v[44:45], off
	global_load_dwordx4 v[70:73], v[48:49], off
	global_load_dwordx4 v[86:89], v[46:47], off offset:-4096
	global_load_dwordx4 v[74:77], v[46:47], off
	v_addc_co_u32_e32 v5, vcc, 0, v5, vcc
	global_load_dwordx4 v[66:69], v[6:7], off
	global_load_dwordx4 v[78:81], v[4:5], off
	s_mov_b64 s[16:17], 0
	s_mov_b32 s10, 0
	v_mov_b32_e32 v2, v115
	v_mov_b32_e32 v3, v115
	v_mov_b32_e32 v4, v115
	v_mov_b32_e32 v5, v115
	v_mov_b32_e32 v6, v115
	v_lshl_add_u64 v[146:147], v[120:121], 0, s[6:7]
	v_mov_b32_e32 v7, v115
	v_mov_b32_e32 v40, v115
	v_mov_b32_e32 v41, v115
	v_mov_b32_e32 v42, v115
	v_mov_b32_e32 v43, v115
	v_mov_b32_e32 v44, v115
	v_mov_b32_e32 v45, v115
	v_mov_b32_e32 v46, v115
	v_mov_b32_e32 v47, v115
	v_mov_b32_e32 v48, v115
	v_mov_b32_e32 v49, v115
	v_mov_b32_e32 v50, v115
	v_mov_b32_e32 v51, v115
	v_mov_b32_e32 v52, v115
	v_mov_b32_e32 v53, v115
	v_mov_b32_e32 v54, v115
	v_mov_b32_e32 v55, v115
	v_mov_b32_e32 v56, v115
	v_mov_b32_e32 v57, v115
	v_mov_b32_e32 v58, v115
	v_mov_b32_e32 v59, v115
	v_mov_b32_e32 v60, v115
	v_mov_b32_e32 v61, v115
	v_mov_b32_e32 v62, v115
	v_mov_b32_e32 v63, v115
	v_mov_b32_e32 v64, v115
	v_mov_b32_e32 v65, v115
	s_waitcnt vmcnt(15)
	ds_write_b128 v150, v[8:11]
	s_waitcnt vmcnt(14)
	ds_write_b128 v150, v[12:15] offset:18432
	s_waitcnt vmcnt(13)
	ds_write_b128 v152, v[16:19]
	s_waitcnt vmcnt(11)
	ds_write_b128 v152, v[24:27] offset:18432
	ds_write_b128 v154, v[20:23]
	s_waitcnt vmcnt(10)
	ds_write_b128 v154, v[28:31] offset:18432
	s_waitcnt vmcnt(9)
	ds_write_b128 v156, v[32:35]
	s_waitcnt vmcnt(8)
	ds_write_b128 v156, v[36:39] offset:18432
	s_waitcnt lgkmcnt(0)
	s_barrier
	ds_read_b128 v[98:101], v171 offset:4608
	ds_read_b128 v[110:113], v171
	ds_read_b128 v[102:105], v172 offset:23040
	ds_read_b128 v[106:109], v172 offset:18432
	v_mov_b32_e32 v8, v115
	v_mov_b32_e32 v9, v115
	v_mov_b32_e32 v10, v115
	v_mov_b32_e32 v11, v115
	v_mov_b32_e32 v12, v115
	v_mov_b32_e32 v13, v115
	v_mov_b32_e32 v14, v115
	v_mov_b32_e32 v15, v115
	v_mov_b32_e32 v16, v115
	v_mov_b32_e32 v17, v115
	v_mov_b32_e32 v18, v115
	v_mov_b32_e32 v19, v115
	v_mov_b32_e32 v20, v115
	v_mov_b32_e32 v21, v115
	v_mov_b32_e32 v22, v115
	v_mov_b32_e32 v23, v115
	v_mov_b32_e32 v24, v115
	v_mov_b32_e32 v25, v115
	v_mov_b32_e32 v26, v115
	v_mov_b32_e32 v27, v115
	v_mov_b32_e32 v28, v115
	v_mov_b32_e32 v29, v115
	v_mov_b32_e32 v30, v115
	v_mov_b32_e32 v31, v115
	v_mov_b32_e32 v32, v115
	v_mov_b32_e32 v33, v115
	v_mov_b32_e32 v34, v115
	v_mov_b32_e32 v35, v115
	v_mov_b32_e32 v36, v115
	v_mov_b32_e32 v37, v115
	v_mov_b32_e32 v38, v115
	v_mov_b32_e32 v39, v115
	v_subrev_u32_e32 v240, s34, v138
	v_subrev_u32_e32 v241, s34, v140
	v_subrev_u32_e32 v242, s34, v142
	v_subrev_u32_e32 v243, s34, v144
	v_subrev_u32_e32 v244, s34, v146
	v_lshlrev_b32_e32 v251, 1, v148
	v_lshl_add_u32 v245, v149, 1, v251
	v_lshl_add_u32 v246, v151, 1, v251
	v_lshl_add_u32 v247, v153, 1, v251
	v_lshl_add_u32 v248, v155, 1, v251
	v_add_u32_e32 v249, v157, v159
	v_add_u32_e32 v250, v158, v159
.LBB0_2272:
	s_add_u32 s62, s34, s16
	s_addc_u32 s63, s35, s17
	s_add_u32 s64, s62, s24
	s_addc_u32 s65, s63, 0
	s_add_u32 s76, s62, s25
	s_addc_u32 s77, s63, 0
	s_waitcnt lgkmcnt(0)
	v_mfma_f32_32x32x16_bf16 v[50:65], v[106:109], v[110:113], v[50:65]
	s_waitcnt vmcnt(7)
	ds_write_b128 v245, v[90:93] offset:36864
	s_waitcnt vmcnt(6)
	ds_write_b128 v245, v[94:97] offset:55296
	v_mfma_f32_32x32x16_bf16 v[34:49], v[102:105], v[110:113], v[34:49]
	s_waitcnt vmcnt(5)
	ds_write_b128 v246, v[82:85] offset:36864
	s_waitcnt vmcnt(3)
	ds_write_b128 v246, v[86:89] offset:55296
	v_mfma_f32_32x32x16_bf16 v[18:33], v[106:109], v[98:101], v[18:33]
	s_waitcnt vmcnt(1)
	ds_write_b128 v247, v[70:73] offset:36864
	s_waitcnt vmcnt(2)
	ds_write_b128 v247, v[74:77] offset:55296
	v_mfma_f32_32x32x16_bf16 v[2:17], v[102:105], v[98:101], v[2:17]
	s_waitcnt vmcnt(0)
	ds_write_b128 v248, v[66:69] offset:36864
	s_waitcnt vmcnt(0)
	ds_write_b128 v248, v[78:81] offset:55296
	ds_read_b128 v[66:69], v249 offset:23072
	ds_read_b128 v[70:73], v250 offset:4640
	global_load_dwordx4 v[90:93], v240, s[62:63]
	s_waitcnt lgkmcnt(0)
	v_mfma_f32_32x32x16_bf16 v[2:17], v[66:69], v[70:73], v[2:17]
	ds_read_b128 v[74:77], v249 offset:18464
	ds_read_b128 v[98:101], v249 offset:18496
	global_load_dwordx4 v[94:97], v244, s[64:65] offset:-4096
	global_load_dwordx4 v[82:85], v241, s[62:63]
	global_load_dwordx4 v[86:89], v244, s[64:65]
	s_waitcnt lgkmcnt(1)
	v_mfma_f32_32x32x16_bf16 v[18:33], v[74:77], v[70:73], v[18:33]
	ds_read_b128 v[70:73], v250 offset:32
	ds_read_b128 v[102:105], v250 offset:64
	s_add_i32 s10, s10, 1
	s_add_u32 s16, s16, 0x4000
	s_addc_u32 s17, s17, 0
	s_waitcnt lgkmcnt(1)
	v_mfma_f32_32x32x16_bf16 v[50:65], v[74:77], v[70:73], v[50:65]
	ds_read_b128 v[174:177], v249 offset:23104
	ds_read_b128 v[178:181], v250 offset:4672
	global_load_dwordx4 v[74:77], v244, s[76:77] offset:-4096
	s_cmp_eq_u32 s16, 0x38000
	global_load_dwordx4 v[78:81], v244, s[76:77]
	v_mfma_f32_32x32x16_bf16 v[34:49], v[66:69], v[70:73], v[34:49]
	global_load_dwordx4 v[70:73], v242, s[62:63]
	global_load_dwordx4 v[66:69], v243, s[62:63]
	ds_read_b128 v[182:185], v249 offset:18528
	ds_read_b128 v[186:189], v250 offset:96
	s_waitcnt lgkmcnt(4)
	v_mfma_f32_32x32x16_bf16 v[50:65], v[98:101], v[102:105], v[50:65]
	ds_read_b128 v[190:193], v249 offset:23136
	ds_read_b128 v[194:197], v250 offset:4704
	s_waitcnt lgkmcnt(0)
	s_barrier
	v_mfma_f32_32x32x16_bf16 v[34:49], v[174:177], v[102:105], v[34:49]
	ds_read_b128 v[106:109], v249 offset:55296
	ds_read_b128 v[110:113], v250 offset:36864
	v_mfma_f32_32x32x16_bf16 v[18:33], v[98:101], v[178:181], v[18:33]
	ds_read_b128 v[102:105], v249 offset:59904
	ds_read_b128 v[98:101], v250 offset:41472
	v_mfma_f32_32x32x16_bf16 v[2:17], v[174:177], v[178:181], v[2:17]
	v_mfma_f32_32x32x16_bf16 v[50:65], v[182:185], v[186:189], v[50:65]
	v_mfma_f32_32x32x16_bf16 v[34:49], v[190:193], v[186:189], v[34:49]
	v_mfma_f32_32x32x16_bf16 v[18:33], v[182:185], v[194:197], v[18:33]
	v_mfma_f32_32x32x16_bf16 v[2:17], v[190:193], v[194:197], v[2:17]
	s_cbranch_scc1 .Ldnu_exit_1
	s_add_u32 s62, s34, s16
	s_addc_u32 s63, s35, s17
	s_add_u32 s64, s62, s24
	s_addc_u32 s65, s63, 0
	s_add_u32 s76, s62, s25
	s_addc_u32 s77, s63, 0
	s_waitcnt lgkmcnt(0)
	v_mfma_f32_32x32x16_bf16 v[50:65], v[106:109], v[110:113], v[50:65]
	s_waitcnt vmcnt(7)
	ds_write_b128 v245, v[90:93]
	s_waitcnt vmcnt(6)
	ds_write_b128 v245, v[94:97] offset:18432
	v_mfma_f32_32x32x16_bf16 v[34:49], v[102:105], v[110:113], v[34:49]
	s_waitcnt vmcnt(5)
	ds_write_b128 v246, v[82:85]
	s_waitcnt vmcnt(3)
	ds_write_b128 v246, v[86:89] offset:18432
	v_mfma_f32_32x32x16_bf16 v[18:33], v[106:109], v[98:101], v[18:33]
	s_waitcnt vmcnt(1)
	ds_write_b128 v247, v[70:73]
	s_waitcnt vmcnt(2)
	ds_write_b128 v247, v[74:77] offset:18432
	v_mfma_f32_32x32x16_bf16 v[2:17], v[102:105], v[98:101], v[2:17]
	s_waitcnt vmcnt(0)
	ds_write_b128 v248, v[66:69]
	s_waitcnt vmcnt(0)
	ds_write_b128 v248, v[78:81] offset:18432
	ds_read_b128 v[66:69], v249 offset:59936
	ds_read_b128 v[70:73], v250 offset:41504
	global_load_dwordx4 v[90:93], v240, s[62:63]
	s_waitcnt lgkmcnt(0)
	v_mfma_f32_32x32x16_bf16 v[2:17], v[66:69], v[70:73], v[2:17]
	ds_read_b128 v[74:77], v249 offset:55328
	ds_read_b128 v[98:101], v249 offset:55360
	global_load_dwordx4 v[94:97], v244, s[64:65] offset:-4096
	global_load_dwordx4 v[82:85], v241, s[62:63]
	global_load_dwordx4 v[86:89], v244, s[64:65]
	s_waitcnt lgkmcnt(1)
	v_mfma_f32_32x32x16_bf16 v[18:33], v[74:77], v[70:73], v[18:33]
	ds_read_b128 v[70:73], v250 offset:36896
	ds_read_b128 v[102:105], v250 offset:36928
	s_add_i32 s10, s10, 1
	s_add_u32 s16, s16, 0x4000
	s_addc_u32 s17, s17, 0
	s_waitcnt lgkmcnt(1)
	v_mfma_f32_32x32x16_bf16 v[50:65], v[74:77], v[70:73], v[50:65]
	ds_read_b128 v[174:177], v249 offset:59968
	ds_read_b128 v[178:181], v250 offset:41536
	global_load_dwordx4 v[74:77], v244, s[76:77] offset:-4096
	s_cmp_eq_u32 s16, 0x38000
	global_load_dwordx4 v[78:81], v244, s[76:77]
	v_mfma_f32_32x32x16_bf16 v[34:49], v[66:69], v[70:73], v[34:49]
	global_load_dwordx4 v[70:73], v242, s[62:63]
	global_load_dwordx4 v[66:69], v243, s[62:63]
	ds_read_b128 v[182:185], v249 offset:55392
	ds_read_b128 v[186:189], v250 offset:36960
	s_waitcnt lgkmcnt(4)
	v_mfma_f32_32x32x16_bf16 v[50:65], v[98:101], v[102:105], v[50:65]
	ds_read_b128 v[190:193], v249 offset:60000
	ds_read_b128 v[194:197], v250 offset:41568
	s_waitcnt lgkmcnt(0)
	s_barrier
	v_mfma_f32_32x32x16_bf16 v[34:49], v[174:177], v[102:105], v[34:49]
	ds_read_b128 v[106:109], v249 offset:18432
	ds_read_b128 v[110:113], v250
	v_mfma_f32_32x32x16_bf16 v[18:33], v[98:101], v[178:181], v[18:33]
	ds_read_b128 v[102:105], v249 offset:23040
	ds_read_b128 v[98:101], v250 offset:4608
	v_mfma_f32_32x32x16_bf16 v[2:17], v[174:177], v[178:181], v[2:17]
	v_mfma_f32_32x32x16_bf16 v[50:65], v[182:185], v[186:189], v[50:65]
	v_mfma_f32_32x32x16_bf16 v[34:49], v[190:193], v[186:189], v[34:49]
	v_mfma_f32_32x32x16_bf16 v[18:33], v[182:185], v[194:197], v[18:33]
	v_mfma_f32_32x32x16_bf16 v[2:17], v[190:193], v[194:197], v[2:17]
	s_cbranch_scc0 .LBB0_2272
.Ldnu_exit_1:
	s_waitcnt lgkmcnt(2)
	v_mfma_f32_32x32x16_bf16 v[50:65], v[106:109], v[110:113], v[50:65]
	s_waitcnt vmcnt(7)
	ds_write_b128 v150, v[90:93] offset:36864
	s_waitcnt vmcnt(6)
	ds_write_b128 v150, v[94:97] offset:55296
	s_lshl_b32 s6, s14, 1
	s_ashr_i32 s7, s6, 31
	s_lshl_b32 s10, s27, 7
	s_lshl_b64 s[6:7], s[6:7], 2
	s_add_u32 s6, s44, s6
	s_waitcnt lgkmcnt(3)
	v_mfma_f32_32x32x16_bf16 v[34:49], v[102:105], v[110:113], v[34:49]
	s_waitcnt vmcnt(5)
	ds_write_b128 v152, v[82:85] offset:36864
	s_waitcnt vmcnt(4)
	ds_write_b128 v152, v[86:89] offset:55296
	s_addc_u32 s7, s45, s7
	s_mov_b32 s16, 0
	s_waitcnt lgkmcnt(4)
	v_mfma_f32_32x32x16_bf16 v[18:33], v[106:109], v[98:101], v[18:33]
	s_waitcnt vmcnt(1)
	ds_write_b128 v154, v[70:73] offset:36864
	ds_write_b128 v154, v[74:77] offset:55296
	v_mfma_f32_32x32x16_bf16 v[2:17], v[102:105], v[98:101], v[2:17]
	s_waitcnt vmcnt(0)
	ds_write_b128 v156, v[66:69] offset:36864
	ds_write_b128 v156, v[78:81] offset:55296
	ds_read_b128 v[66:69], v169 offset:23072
	ds_read_b128 v[70:73], v170 offset:4640
	s_waitcnt lgkmcnt(0)
	v_mfma_f32_32x32x16_bf16 v[2:17], v[66:69], v[70:73], v[2:17]
	ds_read_b128 v[74:77], v169 offset:18464
	ds_read_b128 v[78:81], v169 offset:18496
	s_waitcnt lgkmcnt(1)
	v_mfma_f32_32x32x16_bf16 v[18:33], v[74:77], v[70:73], v[18:33]
	ds_read_b128 v[70:73], v170 offset:32
	ds_read_b128 v[82:85], v170 offset:64
	s_waitcnt lgkmcnt(1)
	v_mfma_f32_32x32x16_bf16 v[50:65], v[74:77], v[70:73], v[50:65]
	ds_read_b128 v[74:77], v169 offset:23104
	ds_read_b128 v[86:89], v170 offset:4672
	v_mfma_f32_32x32x16_bf16 v[34:49], v[66:69], v[70:73], v[34:49]
	ds_read_b128 v[66:69], v169 offset:18528
	ds_read_b128 v[70:73], v170 offset:96
	s_waitcnt lgkmcnt(4)
	v_mfma_f32_32x32x16_bf16 v[50:65], v[78:81], v[82:85], v[50:65]
	ds_read_b128 v[90:93], v169 offset:23136
	ds_read_b128 v[94:97], v170 offset:4704
	s_waitcnt lgkmcnt(0)
	s_barrier
	v_mfma_f32_32x32x16_bf16 v[34:49], v[74:77], v[82:85], v[34:49]
	ds_read_b128 v[82:85], v172 offset:55296
	ds_read_b128 v[98:101], v171 offset:36864
	v_mfma_f32_32x32x16_bf16 v[18:33], v[78:81], v[86:89], v[18:33]
	ds_read_b128 v[78:81], v172 offset:59904
	ds_read_b128 v[102:105], v171 offset:41472
	v_mfma_f32_32x32x16_bf16 v[2:17], v[74:77], v[86:89], v[2:17]
	ds_read_b128 v[74:77], v169 offset:59936
	ds_read_b128 v[86:89], v170 offset:41504
	v_mfma_f32_32x32x16_bf16 v[50:65], v[66:69], v[70:73], v[50:65]
	ds_read_b128 v[106:109], v169 offset:55328
	ds_read_b128 v[110:113], v169 offset:55360
	v_mfma_f32_32x32x16_bf16 v[34:49], v[90:93], v[70:73], v[34:49]
	ds_read_b128 v[70:73], v170 offset:36896
	ds_read_b128 v[138:141], v170 offset:36928
	v_mfma_f32_32x32x16_bf16 v[18:33], v[66:69], v[94:97], v[18:33]
	ds_read_b128 v[66:69], v169 offset:59968
	ds_read_b128 v[142:145], v170 offset:41536
	v_mfma_f32_32x32x16_bf16 v[2:17], v[90:93], v[94:97], v[2:17]
	ds_read_b128 v[90:93], v169 offset:55392
	ds_read_b128 v[94:97], v170 offset:36960
	s_waitcnt lgkmcnt(12)
	v_mfma_f32_32x32x16_bf16 v[50:65], v[82:85], v[98:101], v[50:65]
	ds_read_b128 v[174:177], v169 offset:60000
	ds_read_b128 v[178:181], v170 offset:41568
	s_waitcnt lgkmcnt(0)
	s_barrier
	s_barrier
	v_mfma_f32_32x32x16_bf16 v[34:49], v[78:81], v[98:101], v[34:49]
	v_mfma_f32_32x32x16_bf16 v[18:33], v[82:85], v[102:105], v[18:33]
	v_mfma_f32_32x32x16_bf16 v[2:17], v[78:81], v[102:105], v[2:17]
	v_mfma_f32_32x32x16_bf16 v[50:65], v[106:109], v[70:73], v[50:65]
	v_mfma_f32_32x32x16_bf16 v[34:49], v[74:77], v[70:73], v[34:49]
	v_mfma_f32_32x32x16_bf16 v[18:33], v[106:109], v[86:89], v[18:33]
	v_mfma_f32_32x32x16_bf16 v[2:17], v[74:77], v[86:89], v[2:17]
	v_mfma_f32_32x32x16_bf16 v[50:65], v[110:113], v[138:141], v[50:65]
	v_mfma_f32_32x32x16_bf16 v[34:49], v[66:69], v[138:141], v[34:49]
	v_mfma_f32_32x32x16_bf16 v[18:33], v[110:113], v[142:145], v[18:33]
	v_mfma_f32_32x32x16_bf16 v[2:17], v[66:69], v[142:145], v[2:17]
	v_mfma_f32_32x32x16_bf16 v[50:65], v[90:93], v[94:97], v[50:65]
	s_nop 11
	ds_write_b128 v160, v[50:53]
	ds_write_b128 v160, v[54:57] offset:32
	v_mfma_f32_32x32x16_bf16 v[34:49], v[174:177], v[94:97], v[34:49]
	ds_write_b128 v160, v[58:61] offset:64
	ds_write_b128 v160, v[62:65] offset:96
	v_mfma_f32_32x32x16_bf16 v[18:33], v[90:93], v[178:181], v[18:33]
	s_nop 8
	ds_write_b128 v160, v[34:37] offset:128
	ds_write_b128 v160, v[38:41] offset:160
	v_mfma_f32_32x32x16_bf16 v[2:17], v[174:177], v[178:181], v[2:17]
	ds_write_b128 v160, v[42:45] offset:192
	ds_write_b128 v160, v[46:49] offset:224
	ds_write_b128 v160, v[18:21] offset:16896
	ds_write_b128 v160, v[22:25] offset:16928
	ds_write_b128 v160, v[26:29] offset:16960
	ds_write_b128 v160, v[30:33] offset:16992
	v_or_b32_e32 v20, s10, v1
	s_nop 4
	ds_write_b128 v160, v[2:5] offset:17024
	v_lshl_or_b32 v2, s14, 7, v161
	v_ashrrev_i32_e32 v21, 6, v2
	v_lshl_add_u32 v2, s27, 4, v21
	v_ashrrev_i32_e32 v3, 31, v2
	v_lshlrev_b64 v[2:3], 14, v[2:3]
	v_lshl_add_u64 v[2:3], s[92:93], 0, v[2:3]
	v_lshl_add_u64 v[4:5], v[2:3], 0, v[114:115]
	s_mov_b64 s[14:15], -1
	ds_write_b128 v160, v[6:9] offset:17056
	ds_write_b128 v160, v[10:13] offset:17088
	ds_write_b128 v160, v[14:17] offset:17120
	s_waitcnt lgkmcnt(0)
	s_barrier
	s_branch .LBB0_2275

.LBB0_2476:
	s_lshr_b32 s2, s22, 3
	s_and_b32 s25, s2, 24
	s_lshl_b32 s2, s25, 3
	s_sub_i32 s2, s22, s2
	s_ashr_i32 s24, s2, 3
	s_and_b32 s2, s22, 7
	s_or_b32 s2, s2, s13
	s_or_b32 s23, s2, s25
	s_mul_i32 s6, s23, 0xb0000
	v_mad_i64_i32 v[34:35], s[2:3], s24, v168, v[116:117]
	v_lshl_add_u64 v[36:37], v[118:119], 0, s[6:7]
	v_lshl_add_u64 v[10:11], v[36:37], 0, v[130:131]
	v_lshl_add_u64 v[26:27], v[36:37], 0, v[132:133]
	v_add_co_u32_e32 v28, vcc, s17, v34
	s_waitcnt vmcnt(63) expcnt(7) lgkmcnt(15)
	s_barrier
	global_load_dwordx4 v[2:5], v[10:11], off
	global_load_dwordx4 v[6:9], v[34:35], off
	v_addc_co_u32_e32 v29, vcc, 0, v35, vcc
	v_lshl_add_u64 v[30:31], v[36:37], 0, v[134:135]
	global_load_dwordx4 v[10:13], v[26:27], off
	global_load_dwordx4 v[14:17], v[30:31], off
	global_load_dwordx4 v[18:21], v[28:29], off offset:-4096
	global_load_dwordx4 v[22:25], v[28:29], off
	v_add_co_u32_e32 v38, vcc, s18, v34
	v_lshl_add_u64 v[26:27], v[36:37], 0, v[136:137]
	s_nop 0
	v_addc_co_u32_e32 v39, vcc, 0, v35, vcc
	v_add_co_u32_e32 v44, vcc, s19, v34
	v_lshl_add_u64 v[36:37], v[36:37], 0, s[8:9]
	s_nop 0
	v_addc_co_u32_e32 v45, vcc, 0, v35, vcc
	global_load_dwordx4 v[26:29], v[26:27], off
	v_lshl_add_u64 v[40:41], v[36:37], 0, v[130:131]
	v_lshl_add_u64 v[42:43], v[36:37], 0, v[132:133]
	v_lshl_add_u64 v[46:47], v[36:37], 0, v[134:135]
	v_lshl_add_u64 v[36:37], v[36:37], 0, v[136:137]
	v_add_co_u32_e32 v34, vcc, 0x7000, v34
	global_load_dwordx4 v[30:33], v[38:39], off offset:-4096
	global_load_dwordx4 v[90:93], v[40:41], off
	global_load_dwordx4 v[94:97], v[38:39], off
	global_load_dwordx4 v[82:85], v[42:43], off
	global_load_dwordx4 v[66:69], v[46:47], off
	global_load_dwordx4 v[86:89], v[44:45], off offset:-4096
	global_load_dwordx4 v[74:77], v[44:45], off
	v_addc_co_u32_e32 v35, vcc, 0, v35, vcc
	global_load_dwordx4 v[70:73], v[36:37], off
	global_load_dwordx4 v[78:81], v[34:35], off
	s_and_b32 s2, s12, 7
	s_add_i32 s3, s13, s25
	s_add_i32 s25, s3, s2
	s_mov_b64 s[10:11], 0
	s_mov_b32 s6, 0
	v_mad_u64_u32 v[140:141], s[2:3], s25, v168, v[122:123]
	v_mad_u64_u32 v[142:143], s[2:3], s25, v168, v[124:125]
	v_mad_u64_u32 v[144:145], s[2:3], s25, v168, v[126:127]
	v_mad_u64_u32 v[146:147], s[2:3], s25, v168, v[128:129]
	v_mad_i64_i32 v[148:149], s[2:3], s24, v168, v[120:121]
	v_mov_b32_e32 v34, v115
	v_mov_b32_e32 v35, v115
	v_mov_b32_e32 v36, v115
	v_mov_b32_e32 v37, v115
	v_mov_b32_e32 v38, v115
	v_mov_b32_e32 v39, v115
	v_mov_b32_e32 v40, v115
	v_mov_b32_e32 v41, v115
	v_mov_b32_e32 v42, v115
	v_mov_b32_e32 v43, v115
	v_mov_b32_e32 v44, v115
	v_mov_b32_e32 v45, v115
	v_mov_b32_e32 v46, v115
	v_mov_b32_e32 v47, v115
	v_mov_b32_e32 v48, v115
	v_mov_b32_e32 v49, v115
	v_mov_b32_e32 v50, v115
	v_mov_b32_e32 v51, v115
	v_mov_b32_e32 v52, v115
	v_mov_b32_e32 v53, v115
	v_mov_b32_e32 v54, v115
	v_mov_b32_e32 v55, v115
	v_mov_b32_e32 v56, v115
	v_mov_b32_e32 v57, v115
	v_mov_b32_e32 v58, v115
	v_mov_b32_e32 v59, v115
	v_mov_b32_e32 v60, v115
	s_waitcnt vmcnt(15)
	ds_write_b128 v152, v[2:5]
	s_waitcnt vmcnt(14)
	ds_write_b128 v152, v[6:9] offset:18432
	s_waitcnt vmcnt(13)
	ds_write_b128 v154, v[10:13]
	s_waitcnt vmcnt(11)
	ds_write_b128 v154, v[18:21] offset:18432
	ds_write_b128 v156, v[14:17]
	s_waitcnt vmcnt(10)
	ds_write_b128 v156, v[22:25] offset:18432
	s_waitcnt vmcnt(9)
	ds_write_b128 v158, v[26:29]
	s_waitcnt vmcnt(8)
	ds_write_b128 v158, v[30:33] offset:18432
	s_waitcnt lgkmcnt(0)
	s_barrier
	ds_read_b128 v[106:109], v169 offset:18432
	ds_read_b128 v[98:101], v169 offset:23040
	ds_read_b128 v[110:113], v170
	ds_read_b128 v[102:105], v170 offset:4608
	v_mov_b32_e32 v2, v115
	v_mov_b32_e32 v3, v115
	v_mov_b32_e32 v4, v115
	v_mov_b32_e32 v5, v115
	v_mov_b32_e32 v6, v115
	v_mov_b32_e32 v7, v115
	v_mov_b32_e32 v8, v115
	v_mov_b32_e32 v9, v115
	v_mov_b32_e32 v10, v115
	v_mov_b32_e32 v11, v115
	v_mov_b32_e32 v12, v115
	v_mov_b32_e32 v13, v115
	v_mov_b32_e32 v14, v115
	v_mov_b32_e32 v15, v115
	v_mov_b32_e32 v16, v115
	v_mov_b32_e32 v17, v115
	v_mov_b32_e32 v18, v115
	v_mov_b32_e32 v19, v115
	v_mov_b32_e32 v20, v115
	v_mov_b32_e32 v21, v115
	v_mov_b32_e32 v22, v115
	v_mov_b32_e32 v23, v115
	v_mov_b32_e32 v24, v115
	v_mov_b32_e32 v25, v115
	v_mov_b32_e32 v26, v115
	v_mov_b32_e32 v27, v115
	v_mov_b32_e32 v28, v115
	v_mov_b32_e32 v29, v115
	v_mov_b32_e32 v30, v115
	v_mov_b32_e32 v31, v115
	v_mov_b32_e32 v32, v115
	v_mov_b32_e32 v33, v115
	v_mov_b32_e32 v61, v115
	v_mov_b32_e32 v62, v115
	v_mov_b32_e32 v63, v115
	v_mov_b32_e32 v64, v115
	v_mov_b32_e32 v65, v115
	v_subrev_u32_e32 v240, s34, v140
	v_subrev_u32_e32 v241, s34, v142
	v_subrev_u32_e32 v242, s34, v144
	v_subrev_u32_e32 v243, s34, v146
	v_subrev_u32_e32 v244, s34, v148
	v_lshlrev_b32_e32 v251, 1, v150
	v_lshl_add_u32 v245, v151, 1, v251
	v_lshl_add_u32 v246, v153, 1, v251
	v_lshl_add_u32 v247, v155, 1, v251
	v_lshl_add_u32 v248, v157, 1, v251
	v_add_u32_e32 v249, v160, v159
	v_add_u32_e32 v250, v161, v159
.LBB0_2477:
	s_add_u32 s62, s34, s10
	s_addc_u32 s63, s35, s11
	s_add_u32 s64, s62, s20
	s_addc_u32 s65, s63, 0
	s_add_u32 s76, s62, s21
	s_addc_u32 s77, s63, 0
	s_waitcnt lgkmcnt(1)
	v_mfma_f32_32x32x16_bf16 v[50:65], v[106:109], v[110:113], v[50:65]
	s_waitcnt vmcnt(7)
	ds_write_b128 v245, v[90:93] offset:36864
	s_waitcnt vmcnt(6)
	ds_write_b128 v245, v[94:97] offset:55296
	v_mfma_f32_32x32x16_bf16 v[34:49], v[98:101], v[110:113], v[34:49]
	s_waitcnt vmcnt(5)
	ds_write_b128 v246, v[82:85] offset:36864
	s_waitcnt vmcnt(3)
	ds_write_b128 v246, v[86:89] offset:55296
	s_waitcnt lgkmcnt(4)
	v_mfma_f32_32x32x16_bf16 v[18:33], v[106:109], v[102:105], v[18:33]
	s_waitcnt vmcnt(1)
	ds_write_b128 v247, v[66:69] offset:36864
	s_waitcnt vmcnt(2)
	ds_write_b128 v247, v[74:77] offset:55296
	v_mfma_f32_32x32x16_bf16 v[2:17], v[98:101], v[102:105], v[2:17]
	s_waitcnt vmcnt(0)
	ds_write_b128 v248, v[70:73] offset:36864
	s_waitcnt vmcnt(0)
	ds_write_b128 v248, v[78:81] offset:55296
	ds_read_b128 v[66:69], v249 offset:23072
	ds_read_b128 v[70:73], v250 offset:4640
	global_load_dwordx4 v[90:93], v240, s[62:63]
	s_waitcnt lgkmcnt(0)
	v_mfma_f32_32x32x16_bf16 v[2:17], v[66:69], v[70:73], v[2:17]
	ds_read_b128 v[74:77], v249 offset:18464
	ds_read_b128 v[98:101], v249 offset:18496
	global_load_dwordx4 v[94:97], v244, s[64:65] offset:-4096
	global_load_dwordx4 v[82:85], v241, s[62:63]
	global_load_dwordx4 v[86:89], v244, s[64:65]
	s_waitcnt lgkmcnt(1)
	v_mfma_f32_32x32x16_bf16 v[18:33], v[74:77], v[70:73], v[18:33]
	ds_read_b128 v[70:73], v250 offset:32
	ds_read_b128 v[102:105], v250 offset:64
	s_add_i32 s6, s6, 1
	s_add_u32 s10, s10, 0x4000
	s_addc_u32 s11, s11, 0
	s_cmp_eq_u32 s10, 0xa8000
	s_waitcnt lgkmcnt(1)
	v_mfma_f32_32x32x16_bf16 v[50:65], v[74:77], v[70:73], v[50:65]
	ds_read_b128 v[172:175], v249 offset:23104
	ds_read_b128 v[176:179], v250 offset:4672
	global_load_dwordx4 v[74:77], v244, s[76:77] offset:-4096
	s_nop 0
	global_load_dwordx4 v[78:81], v244, s[76:77]
	v_mfma_f32_32x32x16_bf16 v[34:49], v[66:69], v[70:73], v[34:49]
	global_load_dwordx4 v[66:69], v242, s[62:63]
	global_load_dwordx4 v[70:73], v243, s[62:63]
	ds_read_b128 v[180:183], v249 offset:18528
	ds_read_b128 v[184:187], v250 offset:96
	s_waitcnt lgkmcnt(4)
	v_mfma_f32_32x32x16_bf16 v[50:65], v[98:101], v[102:105], v[50:65]
	ds_read_b128 v[188:191], v249 offset:23136
	ds_read_b128 v[192:195], v250 offset:4704
	s_waitcnt lgkmcnt(0)
	s_barrier
	v_mfma_f32_32x32x16_bf16 v[34:49], v[172:175], v[102:105], v[34:49]
	ds_read_b128 v[106:109], v249 offset:55296
	ds_read_b128 v[110:113], v250 offset:36864
	v_mfma_f32_32x32x16_bf16 v[18:33], v[98:101], v[176:179], v[18:33]
	ds_read_b128 v[98:101], v249 offset:59904
	ds_read_b128 v[102:105], v250 offset:41472
	v_mfma_f32_32x32x16_bf16 v[2:17], v[172:175], v[176:179], v[2:17]
	v_mfma_f32_32x32x16_bf16 v[50:65], v[180:183], v[184:187], v[50:65]
	v_mfma_f32_32x32x16_bf16 v[34:49], v[188:191], v[184:187], v[34:49]
	v_mfma_f32_32x32x16_bf16 v[18:33], v[180:183], v[192:195], v[18:33]
	v_mfma_f32_32x32x16_bf16 v[2:17], v[188:191], v[192:195], v[2:17]
	s_cbranch_scc1 .Ldnu_exit_2
	s_add_u32 s62, s34, s10
	s_addc_u32 s63, s35, s11
	s_add_u32 s64, s62, s20
	s_addc_u32 s65, s63, 0
	s_add_u32 s76, s62, s21
	s_addc_u32 s77, s63, 0
	s_waitcnt lgkmcnt(1)
	v_mfma_f32_32x32x16_bf16 v[50:65], v[106:109], v[110:113], v[50:65]
	s_waitcnt vmcnt(7)
	ds_write_b128 v245, v[90:93]
	s_waitcnt vmcnt(6)
	ds_write_b128 v245, v[94:97] offset:18432
	v_mfma_f32_32x32x16_bf16 v[34:49], v[98:101], v[110:113], v[34:49]
	s_waitcnt vmcnt(5)
	ds_write_b128 v246, v[82:85]
	s_waitcnt vmcnt(3)
	ds_write_b128 v246, v[86:89] offset:18432
	s_waitcnt lgkmcnt(4)
	v_mfma_f32_32x32x16_bf16 v[18:33], v[106:109], v[102:105], v[18:33]
	s_waitcnt vmcnt(1)
	ds_write_b128 v247, v[66:69]
	s_waitcnt vmcnt(2)
	ds_write_b128 v247, v[74:77] offset:18432
	v_mfma_f32_32x32x16_bf16 v[2:17], v[98:101], v[102:105], v[2:17]
	s_waitcnt vmcnt(0)
	ds_write_b128 v248, v[70:73]
	s_waitcnt vmcnt(0)
	ds_write_b128 v248, v[78:81] offset:18432
	ds_read_b128 v[66:69], v249 offset:59936
	ds_read_b128 v[70:73], v250 offset:41504
	global_load_dwordx4 v[90:93], v240, s[62:63]
	s_waitcnt lgkmcnt(0)
	v_mfma_f32_32x32x16_bf16 v[2:17], v[66:69], v[70:73], v[2:17]
	ds_read_b128 v[74:77], v249 offset:55328
	ds_read_b128 v[98:101], v249 offset:55360
	global_load_dwordx4 v[94:97], v244, s[64:65] offset:-4096
	global_load_dwordx4 v[82:85], v241, s[62:63]
	global_load_dwordx4 v[86:89], v244, s[64:65]
	s_waitcnt lgkmcnt(1)
	v_mfma_f32_32x32x16_bf16 v[18:33], v[74:77], v[70:73], v[18:33]
	ds_read_b128 v[70:73], v250 offset:36896
	ds_read_b128 v[102:105], v250 offset:36928
	s_add_i32 s6, s6, 1
	s_add_u32 s10, s10, 0x4000
	s_addc_u32 s11, s11, 0
	s_cmp_eq_u32 s10, 0xa8000
	s_waitcnt lgkmcnt(1)
	v_mfma_f32_32x32x16_bf16 v[50:65], v[74:77], v[70:73], v[50:65]
	ds_read_b128 v[172:175], v249 offset:59968
	ds_read_b128 v[176:179], v250 offset:41536
	global_load_dwordx4 v[74:77], v244, s[76:77] offset:-4096
	s_nop 0
	global_load_dwordx4 v[78:81], v244, s[76:77]
	v_mfma_f32_32x32x16_bf16 v[34:49], v[66:69], v[70:73], v[34:49]
	global_load_dwordx4 v[66:69], v242, s[62:63]
	global_load_dwordx4 v[70:73], v243, s[62:63]
	ds_read_b128 v[180:183], v249 offset:55392
	ds_read_b128 v[184:187], v250 offset:36960
	s_waitcnt lgkmcnt(4)
	v_mfma_f32_32x32x16_bf16 v[50:65], v[98:101], v[102:105], v[50:65]
	ds_read_b128 v[188:191], v249 offset:60000
	ds_read_b128 v[192:195], v250 offset:41568
	s_waitcnt lgkmcnt(0)
	s_barrier
	v_mfma_f32_32x32x16_bf16 v[34:49], v[172:175], v[102:105], v[34:49]
	ds_read_b128 v[106:109], v249 offset:18432
	ds_read_b128 v[110:113], v250
	v_mfma_f32_32x32x16_bf16 v[18:33], v[98:101], v[176:179], v[18:33]
	ds_read_b128 v[98:101], v249 offset:23040
	ds_read_b128 v[102:105], v250 offset:4608
	v_mfma_f32_32x32x16_bf16 v[2:17], v[172:175], v[176:179], v[2:17]
	v_mfma_f32_32x32x16_bf16 v[50:65], v[180:183], v[184:187], v[50:65]
	v_mfma_f32_32x32x16_bf16 v[34:49], v[188:191], v[184:187], v[34:49]
	v_mfma_f32_32x32x16_bf16 v[18:33], v[180:183], v[192:195], v[18:33]
	v_mfma_f32_32x32x16_bf16 v[2:17], v[188:191], v[192:195], v[2:17]
	s_cbranch_scc0 .LBB0_2477
.Ldnu_exit_2:
	s_waitcnt lgkmcnt(2)
	v_mfma_f32_32x32x16_bf16 v[50:65], v[106:109], v[110:113], v[50:65]
	s_waitcnt vmcnt(7)
	ds_write_b128 v152, v[90:93] offset:36864
	s_waitcnt vmcnt(6)
	ds_write_b128 v152, v[94:97] offset:55296
	s_lshl_b32 s6, s23, 7
	s_mov_b64 s[10:11], -1
	s_waitcnt lgkmcnt(3)
	v_mfma_f32_32x32x16_bf16 v[34:49], v[98:101], v[110:113], v[34:49]
	s_waitcnt vmcnt(5)
	ds_write_b128 v154, v[82:85] offset:36864
	s_waitcnt vmcnt(4)
	ds_write_b128 v154, v[86:89] offset:55296
	s_waitcnt lgkmcnt(4)
	v_mfma_f32_32x32x16_bf16 v[18:33], v[106:109], v[102:105], v[18:33]
	s_waitcnt vmcnt(1)
	ds_write_b128 v156, v[66:69] offset:36864
	ds_write_b128 v156, v[74:77] offset:55296
	v_mfma_f32_32x32x16_bf16 v[2:17], v[98:101], v[102:105], v[2:17]
	s_waitcnt vmcnt(0)
	ds_write_b128 v158, v[70:73] offset:36864
	ds_write_b128 v158, v[78:81] offset:55296
	ds_read_b128 v[66:69], v162 offset:23072
	ds_read_b128 v[70:73], v163 offset:4640
	s_waitcnt lgkmcnt(0)
	v_mfma_f32_32x32x16_bf16 v[2:17], v[66:69], v[70:73], v[2:17]
	ds_read_b128 v[74:77], v162 offset:18464
	ds_read_b128 v[78:81], v162 offset:18496
	s_waitcnt lgkmcnt(1)
	v_mfma_f32_32x32x16_bf16 v[18:33], v[74:77], v[70:73], v[18:33]
	ds_read_b128 v[70:73], v163 offset:32
	ds_read_b128 v[82:85], v163 offset:64
	s_waitcnt lgkmcnt(1)
	v_mfma_f32_32x32x16_bf16 v[50:65], v[74:77], v[70:73], v[50:65]
	ds_read_b128 v[74:77], v162 offset:23104
	ds_read_b128 v[86:89], v163 offset:4672
	v_mfma_f32_32x32x16_bf16 v[34:49], v[66:69], v[70:73], v[34:49]
	ds_read_b128 v[66:69], v162 offset:18528
	ds_read_b128 v[70:73], v163 offset:96
	s_waitcnt lgkmcnt(4)
	v_mfma_f32_32x32x16_bf16 v[50:65], v[78:81], v[82:85], v[50:65]
	ds_read_b128 v[90:93], v162 offset:23136
	ds_read_b128 v[94:97], v163 offset:4704
	s_waitcnt lgkmcnt(0)
	s_barrier
	v_mfma_f32_32x32x16_bf16 v[34:49], v[74:77], v[82:85], v[34:49]
	ds_read_b128 v[82:85], v169 offset:55296
	ds_read_b128 v[98:101], v170 offset:36864
	v_mfma_f32_32x32x16_bf16 v[18:33], v[78:81], v[86:89], v[18:33]
	ds_read_b128 v[78:81], v169 offset:59904
	ds_read_b128 v[102:105], v170 offset:41472
	v_mfma_f32_32x32x16_bf16 v[2:17], v[74:77], v[86:89], v[2:17]
	ds_read_b128 v[74:77], v162 offset:59936
	ds_read_b128 v[86:89], v163 offset:41504
	v_mfma_f32_32x32x16_bf16 v[50:65], v[66:69], v[70:73], v[50:65]
	ds_read_b128 v[106:109], v162 offset:55328
	ds_read_b128 v[110:113], v162 offset:55360
	v_mfma_f32_32x32x16_bf16 v[34:49], v[90:93], v[70:73], v[34:49]
	ds_read_b128 v[70:73], v163 offset:36896
	ds_read_b128 v[140:143], v163 offset:36928
	v_mfma_f32_32x32x16_bf16 v[18:33], v[66:69], v[94:97], v[18:33]
	ds_read_b128 v[66:69], v162 offset:59968
	ds_read_b128 v[144:147], v163 offset:41536
	v_mfma_f32_32x32x16_bf16 v[2:17], v[90:93], v[94:97], v[2:17]
	ds_read_b128 v[90:93], v162 offset:55392
	ds_read_b128 v[94:97], v163 offset:36960
	s_waitcnt lgkmcnt(12)
	v_mfma_f32_32x32x16_bf16 v[50:65], v[82:85], v[98:101], v[50:65]
	ds_read_b128 v[172:175], v162 offset:60000
	ds_read_b128 v[176:179], v163 offset:41568
	s_waitcnt lgkmcnt(0)
	s_barrier
	s_barrier
	v_mfma_f32_32x32x16_bf16 v[34:49], v[78:81], v[98:101], v[34:49]
	v_mfma_f32_32x32x16_bf16 v[18:33], v[82:85], v[102:105], v[18:33]
	v_mfma_f32_32x32x16_bf16 v[2:17], v[78:81], v[102:105], v[2:17]
	v_mfma_f32_32x32x16_bf16 v[50:65], v[106:109], v[70:73], v[50:65]
	v_mfma_f32_32x32x16_bf16 v[34:49], v[74:77], v[70:73], v[34:49]
	v_mfma_f32_32x32x16_bf16 v[18:33], v[106:109], v[86:89], v[18:33]
	v_mfma_f32_32x32x16_bf16 v[2:17], v[74:77], v[86:89], v[2:17]
	v_mfma_f32_32x32x16_bf16 v[50:65], v[110:113], v[140:143], v[50:65]
	v_mfma_f32_32x32x16_bf16 v[34:49], v[66:69], v[140:143], v[34:49]
	v_mfma_f32_32x32x16_bf16 v[18:33], v[110:113], v[144:147], v[18:33]
	v_mfma_f32_32x32x16_bf16 v[2:17], v[66:69], v[144:147], v[2:17]
	v_mfma_f32_32x32x16_bf16 v[50:65], v[90:93], v[94:97], v[50:65]
	s_nop 11
	ds_write_b128 v164, v[50:53]
	ds_write_b128 v164, v[54:57] offset:32
	v_mfma_f32_32x32x16_bf16 v[34:49], v[172:175], v[94:97], v[34:49]
	ds_write_b128 v164, v[58:61] offset:64
	ds_write_b128 v164, v[62:65] offset:96
	v_mfma_f32_32x32x16_bf16 v[18:33], v[90:93], v[176:179], v[18:33]
	s_nop 8
	ds_write_b128 v164, v[34:37] offset:128
	ds_write_b128 v164, v[38:41] offset:160
	v_mfma_f32_32x32x16_bf16 v[2:17], v[172:175], v[176:179], v[2:17]
	ds_write_b128 v164, v[42:45] offset:192
	ds_write_b128 v164, v[46:49] offset:224
	ds_write_b128 v164, v[18:21] offset:16896
	ds_write_b128 v164, v[22:25] offset:16928
	ds_write_b128 v164, v[26:29] offset:16960
	ds_write_b128 v164, v[30:33] offset:16992
	s_nop 5
	ds_write_b128 v164, v[2:5] offset:17024
	v_lshl_or_b32 v4, s24, 7, v165
	s_load_dwordx4 s[24:27], s[0:1], 0xe0
	ds_write_b128 v164, v[6:9] offset:17056
	v_ashrrev_i32_e32 v7, 6, v4
	v_lshl_add_u32 v2, s23, 4, v7
	v_ashrrev_i32_e32 v3, 31, v2
	v_ashrrev_i32_e32 v5, 31, v4
	v_lshlrev_b64 v[2:3], 14, v[2:3]
	v_or_b32_e32 v6, s6, v1
	v_lshl_add_u64 v[2:3], s[92:93], 0, v[2:3]
	s_waitcnt lgkmcnt(0)
	v_lshl_add_u64 v[4:5], v[4:5], 2, s[26:27]
	s_or_b32 s23, s6, 32
	s_or_b32 s24, s6, 40
	s_or_b32 s25, s6, 48
	s_or_b32 s26, s6, 56
	s_mov_b32 s27, 0
	ds_write_b128 v164, v[10:13] offset:17088
	ds_write_b128 v164, v[14:17] offset:17120
	s_waitcnt lgkmcnt(0)
	s_barrier
